# K=1024 GEMM epilogue: parameter block loaded at unit set-up (before the K-loop) instead of a blocking load after it
# baseline (speedup 1.0000x reference)
; #define PG8_STAGE(bufoff, gbase, voff) do { _Pragma("unroll") for (int _i = 0; _i < 2; ++_i) \
;         __builtin_amdgcn_global_load_lds((const unsigned*)((const char*)(gbase) + (voff)[_i]), (PG8_LAS unsigned*)(lds + (bufoff) + ldsw + _i * 8192), 16, 0, 0); } while (0)
; #define PG8_LDA(dst, b, h) do { _Pragma("unroll") for (int m = 0; m < 4; ++m) _Pragma("unroll") for (int k = 0; k < 2; ++k) dst[m][k] = *(const PG8_LAS bf16x8*)(lds + PG8_SA(b, h) + aoff + m * 2048 + k * 1024); } while (0)
; #define PG8_LDB(dst, b, h) do { _Pragma("unroll") for (int n = 0; n < 2; ++n) _Pragma("unroll") for (int k = 0; k < 2; ++k) dst[n][k] = *(const PG8_LAS bf16x8*)(lds + PG8_SB(b, h) + boff + n * 2048 + k * 1024); } while (0)
; #define PG8_WAIT_V(n) asm volatile("s_waitcnt vmcnt(" #n ")" ::: "memory")
; #define PG8_WAIT_L(n) asm volatile("s_waitcnt lgkmcnt(" #n ")" ::: "memory")
; #define PG8_BAR __builtin_amdgcn_s_barrier()
; #define PG8_SCHED __builtin_amdgcn_sched_barrier(0)
; template <class Epi, class Sched, bool ALIGN_EPI = false, bool SP2 = false>
; __device__ __forceinline__ void gemm_phase(PG8_LAS unsigned char* lds, const Gemm g, const Sched& S, const Epi& E, const int wave0) {
;     ...
;     for (;;) {
;         const bool has_next = S.next(ui + 1, nxt);
;         const char* nA = has_next ? (const char*)g.A + (size_t)nxt.pm * tstep : cA; const char* nB = has_next ? (const char*)g.Bt + (size_t)nxt.pn * tstep : cB;
;         for (int t = 0; t < nt; t += 2) {
;             const bool last = (t == nt - 2);
;             const char* a1 = cA + (size_t)(t + 1) * kstep;
;             const char* a2 = last ? nA : cA + (size_t)(t + 2) * kstep; const char* b2 = last ? nB : cB + (size_t)(t + 2) * kstep;
;             const char* a3 = a2 + kstep; const char* b3 = b2 + kstep;
;             if (last && has_next) S.a_ready(nxt);
;             if constexpr (SP2) {
;             PG8_LDB(B0, 0, 0); PG8_LDB(B1, 0, 1); PG8_SCHED; PG8_LDA(At, 0, 0); PG8_STAGE(PG8_SA(1, 1), a1 + hstep, voffA);
;             PG8_WAIT_V(8); PG8_WAIT_L(0); PG8_BAR; PG8_MMA(0, 0, At, B0); PG8_MMA(0, 1, At, B1); PG8_BAR; PG8_SCHED;
;             PG8_LDA(At, 0, 1); PG8_STAGE(PG8_SB(0, 0), b2, voffB); PG8_STAGE(PG8_SB(0, 1), b2 + hstep, voffB); PG8_STAGE(PG8_SA(0, 0), a2, voffA);
;             PG8_WAIT_V(8); PG8_WAIT_L(0); PG8_BAR; PG8_MMA(1, 0, At, B0); PG8_MMA(1, 1, At, B1); PG8_BAR; PG8_SCHED;
.LBB0_1139:
	s_ashr_i32 s49, s48, 31
	s_lshl_b64 s[18:19], s[48:49], 19
	s_add_u32 s50, s36, s18
	s_addc_u32 s51, s37, s19
	s_and_b64 s[18:19], s[6:7], exec
	s_cselect_b32 s9, s51, s11
	s_cselect_b32 s49, s50, s10
	s_ashr_i32 s47, s46, 31
	s_lshl_b64 s[18:19], s[46:47], 19
	s_add_u32 s52, s38, s18
	s_addc_u32 s53, s39, s19
	s_and_b64 s[18:19], s[6:7], exec
	s_cselect_b32 s47, s53, s57
	s_cselect_b32 s60, s52, s56
	s_add_u32 s10, s10, 0x40080
	s_addc_u32 s11, s11, 0
	s_add_u32 s61, s56, 0x100
	s_addc_u32 s62, s57, 0
	s_mov_b32 s63, -2
	global_load_dwordx4 v[192:195], v215, s[40:41] offset:1024
	global_load_dwordx4 v[196:199], v215, s[40:41] offset:1064
	global_load_dwordx4 v[200:203], v215, s[40:41] offset:1048
	s_waitcnt lgkmcnt(0)
	s_add_u32 s18, s10, 0xfffc0080
	s_addc_u32 s19, s11, -1
	s_add_i32 s64, 0, 0x10000
	s_cmp_eq_u32 s63, 12
	s_cselect_b32 s59, s9, s19
	s_cselect_b32 s58, s49, s18
	s_cselect_b32 s57, s47, s62
	s_cselect_b32 s56, s60, s61
	s_add_i32 s65, 0, 0x14000
	v_add_u32_e32 v140, s64, v247
	v_add_u32_e32 v156, s65, v247
	ds_read_b128 v[64:67], v140
	ds_read_b128 v[68:71], v140 offset:1024
	ds_read_b128 v[136:139], v140 offset:2048
	ds_read_b128 v[140:143], v140 offset:3072
	ds_read_b128 v[144:147], v156
	ds_read_b128 v[148:151], v156 offset:1024
	ds_read_b128 v[152:155], v156 offset:2048
	ds_read_b128 v[156:159], v156 offset:3072
	s_add_i32 m0, s33, 0xc000
	ds_read_b128 v[160:163], v245
	ds_read_b128 v[164:167], v245 offset:1024
	ds_read_b128 v[168:171], v245 offset:2048
	ds_read_b128 v[172:175], v245 offset:3072
	ds_read_b128 v[176:179], v245 offset:4096
	ds_read_b128 v[180:183], v245 offset:5120
	ds_read_b128 v[184:187], v245 offset:6144
	ds_read_b128 v[188:191], v245 offset:7168
	global_load_lds_dwordx4 v224, s[10:11]
	s_add_i32 m0, s33, 0xe000
	s_nop 0
	global_load_lds_dwordx4 v226, s[10:11]
	s_waitcnt vmcnt(8)
	s_waitcnt lgkmcnt(0)
	s_barrier
	s_setprio 1
	v_mfma_f32_16x16x32_bf16 v[132:135], v[64:67], v[160:163], 0
	v_mfma_f32_16x16x32_bf16 v[128:131], v[136:139], v[160:163], 0
	v_mfma_f32_16x16x32_bf16 v[116:119], v[64:67], v[168:171], 0
	v_mfma_f32_16x16x32_bf16 v[108:111], v[136:139], v[168:171], 0
	v_mfma_f32_16x16x32_bf16 v[100:103], v[64:67], v[176:179], 0
	v_mfma_f32_16x16x32_bf16 v[92:95], v[136:139], v[176:179], 0
	v_mfma_f32_16x16x32_bf16 v[84:87], v[64:67], v[184:187], 0
	v_mfma_f32_16x16x32_bf16 v[76:79], v[136:139], v[184:187], 0
	v_mfma_f32_16x16x32_bf16 v[132:135], v[68:71], v[164:167], v[132:135]
	v_mfma_f32_16x16x32_bf16 v[128:131], v[140:143], v[164:167], v[128:131]
	v_mfma_f32_16x16x32_bf16 v[116:119], v[68:71], v[172:175], v[116:119]
	v_mfma_f32_16x16x32_bf16 v[108:111], v[140:143], v[172:175], v[108:111]
	v_mfma_f32_16x16x32_bf16 v[100:103], v[68:71], v[180:183], v[100:103]
	v_mfma_f32_16x16x32_bf16 v[92:95], v[140:143], v[180:183], v[92:95]
	v_mfma_f32_16x16x32_bf16 v[84:87], v[68:71], v[188:191], v[84:87]
	v_mfma_f32_16x16x32_bf16 v[76:79], v[140:143], v[188:191], v[76:79]
	v_mfma_f32_16x16x32_bf16 v[124:127], v[144:147], v[160:163], 0
	v_mfma_f32_16x16x32_bf16 v[120:123], v[152:155], v[160:163], 0
	v_mfma_f32_16x16x32_bf16 v[112:115], v[144:147], v[168:171], 0
	v_mfma_f32_16x16x32_bf16 v[104:107], v[152:155], v[168:171], 0
	v_mfma_f32_16x16x32_bf16 v[96:99], v[144:147], v[176:179], 0
	v_mfma_f32_16x16x32_bf16 v[88:91], v[152:155], v[176:179], 0
	v_mfma_f32_16x16x32_bf16 v[80:83], v[144:147], v[184:187], 0
	v_mfma_f32_16x16x32_bf16 v[72:75], v[152:155], v[184:187], 0
	v_mfma_f32_16x16x32_bf16 v[124:127], v[148:151], v[164:167], v[124:127]
	v_mfma_f32_16x16x32_bf16 v[120:123], v[156:159], v[164:167], v[120:123]
	v_mfma_f32_16x16x32_bf16 v[112:115], v[148:151], v[172:175], v[112:115]
	v_mfma_f32_16x16x32_bf16 v[104:107], v[156:159], v[172:175], v[104:107]
	v_mfma_f32_16x16x32_bf16 v[96:99], v[148:151], v[180:183], v[96:99]
	v_mfma_f32_16x16x32_bf16 v[88:91], v[156:159], v[180:183], v[88:91]
	v_mfma_f32_16x16x32_bf16 v[80:83], v[148:151], v[188:191], v[80:83]
	v_mfma_f32_16x16x32_bf16 v[72:75], v[156:159], v[188:191], v[72:75]
	s_setprio 0
	s_barrier
	s_add_i32 s18, s64, s95
	s_mov_b32 m0, s18
	ds_read_b128 v[160:163], v245 offset:16384
	ds_read_b128 v[164:167], v245 offset:17408
	ds_read_b128 v[168:171], v245 offset:18432
	ds_read_b128 v[172:175], v245 offset:19456
	ds_read_b128 v[176:179], v245 offset:20480
	ds_read_b128 v[180:183], v245 offset:21504
	ds_read_b128 v[184:187], v245 offset:22528
	ds_read_b128 v[188:191], v245 offset:23552
	global_load_lds_dwordx4 v218, s[56:57]
	s_add_i32 m0, s18, 0x2000
	s_add_u32 s18, s56, 0x40000
	s_addc_u32 s19, s57, 0
	s_add_i32 s64, s65, s95
	global_load_lds_dwordx4 v222, s[56:57]
	s_mov_b32 m0, s64
	s_nop 0
	global_load_lds_dwordx4 v218, s[18:19]
	s_add_i32 m0, s64, 0x2000
	s_nop 0
	global_load_lds_dwordx4 v222, s[18:19]
	s_mov_b32 m0, s33
	s_nop 0
	global_load_lds_dwordx4 v216, s[58:59]
	s_mov_b32 m0, s82
	s_nop 0
	global_load_lds_dwordx4 v220, s[58:59]
	s_waitcnt vmcnt(8)
	s_waitcnt lgkmcnt(0)
	s_barrier
; #define PG8_STAGE(bufoff, gbase, voff) do { _Pragma("unroll") for (int _i = 0; _i < 2; ++_i) \
;         __builtin_amdgcn_global_load_lds((const unsigned*)((const char*)(gbase) + (voff)[_i]), (PG8_LAS unsigned*)(lds + (bufoff) + ldsw + _i * 8192), 16, 0, 0); } while (0)
; #define PG8_LDA(dst, b, h) do { _Pragma("unroll") for (int m = 0; m < 4; ++m) _Pragma("unroll") for (int k = 0; k < 2; ++k) dst[m][k] = *(const PG8_LAS bf16x8*)(lds + PG8_SA(b, h) + aoff + m * 2048 + k * 1024); } while (0)
; #define PG8_LDB(dst, b, h) do { _Pragma("unroll") for (int n = 0; n < 2; ++n) _Pragma("unroll") for (int k = 0; k < 2; ++k) dst[n][k] = *(const PG8_LAS bf16x8*)(lds + PG8_SB(b, h) + boff + n * 2048 + k * 1024); } while (0)
; #define PG8_MMA(ai, bj, At, Bt) do { __builtin_amdgcn_s_setprio(1); _Pragma("unroll") for (int m = 0; m < 4; ++m) _Pragma("unroll") for (int n = 0; n < 2; ++n) _Pragma("unroll") for (int k = 0; k < 2; ++k) \
;         acc[ai][bj][m][n] = __builtin_amdgcn_mfma_f32_16x16x32_bf16(Bt[n][k], At[m][k], acc[ai][bj][m][n], 0, 0, 0); __builtin_amdgcn_s_setprio(0); } while (0)
; #define PG8_WAIT_V(n) asm volatile("s_waitcnt vmcnt(" #n ")" ::: "memory")
; #define PG8_WAIT_L(n) asm volatile("s_waitcnt lgkmcnt(" #n ")" ::: "memory")
; #define PG8_BAR __builtin_amdgcn_s_barrier()
; #define PG8_SCHED __builtin_amdgcn_sched_barrier(0)
; template <class Epi, class Sched, bool ALIGN_EPI = false, bool SP2 = false>
; __device__ __forceinline__ void gemm_phase(PG8_LAS unsigned char* lds, const Gemm g, const Sched& S, const Epi& E, const int wave0) {
;     ...
;             PG8_WAIT_V(8); PG8_WAIT_L(0); PG8_BAR; PG8_MMA(0, 0, At, B0); PG8_MMA(0, 1, At, B1); PG8_BAR; PG8_SCHED;
;             PG8_LDA(At, 0, 1); PG8_STAGE(PG8_SB(0, 0), b2, voffB); PG8_STAGE(PG8_SB(0, 1), b2 + hstep, voffB); PG8_STAGE(PG8_SA(0, 0), a2, voffA);
;             PG8_WAIT_V(8); PG8_WAIT_L(0); PG8_BAR; PG8_MMA(1, 0, At, B0); PG8_MMA(1, 1, At, B1); PG8_BAR; PG8_SCHED;
;             PG8_LDB(B0, 1, 0); PG8_LDB(B1, 1, 1); PG8_SCHED; PG8_LDA(At, 1, 0); PG8_STAGE(PG8_SA(0, 1), a2 + hstep, voffA);
;             PG8_WAIT_V(8); PG8_WAIT_L(0); PG8_BAR; PG8_MMA(0, 0, At, B0); PG8_MMA(0, 1, At, B1); PG8_BAR; PG8_SCHED;
	s_setprio 1
	v_mfma_f32_16x16x32_bf16 v[60:63], v[64:67], v[160:163], 0
	v_mfma_f32_16x16x32_bf16 v[52:55], v[136:139], v[160:163], 0
	v_mfma_f32_16x16x32_bf16 v[44:47], v[64:67], v[168:171], 0
	v_mfma_f32_16x16x32_bf16 v[36:39], v[136:139], v[168:171], 0
	v_mfma_f32_16x16x32_bf16 v[28:31], v[64:67], v[176:179], 0
	v_mfma_f32_16x16x32_bf16 v[20:23], v[136:139], v[176:179], 0
	v_mfma_f32_16x16x32_bf16 v[12:15], v[64:67], v[184:187], 0
	v_mfma_f32_16x16x32_bf16 v[4:7], v[136:139], v[184:187], 0
	v_mfma_f32_16x16x32_bf16 v[60:63], v[68:71], v[164:167], v[60:63]
	v_mfma_f32_16x16x32_bf16 v[52:55], v[140:143], v[164:167], v[52:55]
	v_mfma_f32_16x16x32_bf16 v[44:47], v[68:71], v[172:175], v[44:47]
	v_mfma_f32_16x16x32_bf16 v[36:39], v[140:143], v[172:175], v[36:39]
	v_mfma_f32_16x16x32_bf16 v[28:31], v[68:71], v[180:183], v[28:31]
	v_mfma_f32_16x16x32_bf16 v[20:23], v[140:143], v[180:183], v[20:23]
	v_mfma_f32_16x16x32_bf16 v[12:15], v[68:71], v[188:191], v[12:15]
	v_mfma_f32_16x16x32_bf16 v[4:7], v[140:143], v[188:191], v[4:7]
	v_mfma_f32_16x16x32_bf16 v[56:59], v[144:147], v[160:163], 0
	v_mfma_f32_16x16x32_bf16 v[48:51], v[152:155], v[160:163], 0
	v_mfma_f32_16x16x32_bf16 v[40:43], v[144:147], v[168:171], 0
	v_mfma_f32_16x16x32_bf16 v[32:35], v[152:155], v[168:171], 0
	v_mfma_f32_16x16x32_bf16 v[24:27], v[144:147], v[176:179], 0
	v_mfma_f32_16x16x32_bf16 v[16:19], v[152:155], v[176:179], 0
	v_mfma_f32_16x16x32_bf16 v[8:11], v[144:147], v[184:187], 0
	v_mfma_f32_16x16x32_bf16 v[0:3], v[152:155], v[184:187], 0
	v_mfma_f32_16x16x32_bf16 v[56:59], v[148:151], v[164:167], v[56:59]
	v_mfma_f32_16x16x32_bf16 v[48:51], v[156:159], v[164:167], v[48:51]
	v_mfma_f32_16x16x32_bf16 v[40:43], v[148:151], v[172:175], v[40:43]
	v_mfma_f32_16x16x32_bf16 v[32:35], v[156:159], v[172:175], v[32:35]
	v_mfma_f32_16x16x32_bf16 v[24:27], v[148:151], v[180:183], v[24:27]
	v_mfma_f32_16x16x32_bf16 v[16:19], v[156:159], v[180:183], v[16:19]
	v_mfma_f32_16x16x32_bf16 v[8:11], v[148:151], v[188:191], v[8:11]
	v_mfma_f32_16x16x32_bf16 v[0:3], v[156:159], v[188:191], v[0:3]
	s_setprio 0
	s_barrier
	s_add_i32 s64, 0, 0x18000
	s_add_i32 s65, 0, 0x1c000
	v_add_u32_e32 v140, s64, v247
	v_add_u32_e32 v156, s65, v247
	ds_read_b128 v[64:67], v140
	ds_read_b128 v[68:71], v140 offset:1024
	ds_read_b128 v[136:139], v140 offset:2048
	ds_read_b128 v[140:143], v140 offset:3072
	ds_read_b128 v[144:147], v156
	ds_read_b128 v[148:151], v156 offset:1024
	ds_read_b128 v[152:155], v156 offset:2048
	ds_read_b128 v[156:159], v156 offset:3072
	s_add_u32 s18, s58, 0x40000
	s_addc_u32 s19, s59, 0
	s_mov_b32 m0, s16
	ds_read_b128 v[160:163], v245 offset:32768
	ds_read_b128 v[164:167], v245 offset:33792
	ds_read_b128 v[168:171], v245 offset:34816
	ds_read_b128 v[172:175], v245 offset:35840
	ds_read_b128 v[176:179], v245 offset:36864
	ds_read_b128 v[180:183], v245 offset:37888
	ds_read_b128 v[184:187], v245 offset:38912
	ds_read_b128 v[188:191], v245 offset:39936
	global_load_lds_dwordx4 v216, s[18:19]
	s_mov_b32 m0, s83
	s_nop 0
	global_load_lds_dwordx4 v220, s[18:19]
	s_waitcnt vmcnt(8)
	s_waitcnt lgkmcnt(0)
	s_barrier
	s_setprio 1
	v_mfma_f32_16x16x32_bf16 v[132:135], v[64:67], v[160:163], v[132:135]
	v_mfma_f32_16x16x32_bf16 v[128:131], v[136:139], v[160:163], v[128:131]
	v_mfma_f32_16x16x32_bf16 v[116:119], v[64:67], v[168:171], v[116:119]
	v_mfma_f32_16x16x32_bf16 v[108:111], v[136:139], v[168:171], v[108:111]
	v_mfma_f32_16x16x32_bf16 v[100:103], v[64:67], v[176:179], v[100:103]
	v_mfma_f32_16x16x32_bf16 v[92:95], v[136:139], v[176:179], v[92:95]
	v_mfma_f32_16x16x32_bf16 v[84:87], v[64:67], v[184:187], v[84:87]
	v_mfma_f32_16x16x32_bf16 v[76:79], v[136:139], v[184:187], v[76:79]
	v_mfma_f32_16x16x32_bf16 v[132:135], v[68:71], v[164:167], v[132:135]
	v_mfma_f32_16x16x32_bf16 v[128:131], v[140:143], v[164:167], v[128:131]
	v_mfma_f32_16x16x32_bf16 v[116:119], v[68:71], v[172:175], v[116:119]
	v_mfma_f32_16x16x32_bf16 v[108:111], v[140:143], v[172:175], v[108:111]
	v_mfma_f32_16x16x32_bf16 v[100:103], v[68:71], v[180:183], v[100:103]
	v_mfma_f32_16x16x32_bf16 v[92:95], v[140:143], v[180:183], v[92:95]
	v_mfma_f32_16x16x32_bf16 v[84:87], v[68:71], v[188:191], v[84:87]
	v_mfma_f32_16x16x32_bf16 v[76:79], v[140:143], v[188:191], v[76:79]
	v_mfma_f32_16x16x32_bf16 v[124:127], v[144:147], v[160:163], v[124:127]
	v_mfma_f32_16x16x32_bf16 v[120:123], v[152:155], v[160:163], v[120:123]
	v_mfma_f32_16x16x32_bf16 v[112:115], v[144:147], v[168:171], v[112:115]
	v_mfma_f32_16x16x32_bf16 v[104:107], v[152:155], v[168:171], v[104:107]
	v_mfma_f32_16x16x32_bf16 v[96:99], v[144:147], v[176:179], v[96:99]
	v_mfma_f32_16x16x32_bf16 v[88:91], v[152:155], v[176:179], v[88:91]
	v_mfma_f32_16x16x32_bf16 v[80:83], v[144:147], v[184:187], v[80:83]
	v_mfma_f32_16x16x32_bf16 v[72:75], v[152:155], v[184:187], v[72:75]
	v_mfma_f32_16x16x32_bf16 v[124:127], v[148:151], v[164:167], v[124:127]
	v_mfma_f32_16x16x32_bf16 v[120:123], v[156:159], v[164:167], v[120:123]
	v_mfma_f32_16x16x32_bf16 v[112:115], v[148:151], v[172:175], v[112:115]
	v_mfma_f32_16x16x32_bf16 v[104:107], v[156:159], v[172:175], v[104:107]
	v_mfma_f32_16x16x32_bf16 v[96:99], v[148:151], v[180:183], v[96:99]
	v_mfma_f32_16x16x32_bf16 v[88:91], v[156:159], v[180:183], v[88:91]
	v_mfma_f32_16x16x32_bf16 v[80:83], v[148:151], v[188:191], v[80:83]
	v_mfma_f32_16x16x32_bf16 v[72:75], v[156:159], v[188:191], v[72:75]
	s_setprio 0
	s_barrier
; #define PG8_STAGE(bufoff, gbase, voff) do { _Pragma("unroll") for (int _i = 0; _i < 2; ++_i) \
;         __builtin_amdgcn_global_load_lds((const unsigned*)((const char*)(gbase) + (voff)[_i]), (PG8_LAS unsigned*)(lds + (bufoff) + ldsw + _i * 8192), 16, 0, 0); } while (0)
; #define PG8_LDA(dst, b, h) do { _Pragma("unroll") for (int m = 0; m < 4; ++m) _Pragma("unroll") for (int k = 0; k < 2; ++k) dst[m][k] = *(const PG8_LAS bf16x8*)(lds + PG8_SA(b, h) + aoff + m * 2048 + k * 1024); } while (0)
; #define PG8_LDB(dst, b, h) do { _Pragma("unroll") for (int n = 0; n < 2; ++n) _Pragma("unroll") for (int k = 0; k < 2; ++k) dst[n][k] = *(const PG8_LAS bf16x8*)(lds + PG8_SB(b, h) + boff + n * 2048 + k * 1024); } while (0)
; #define PG8_MMA(ai, bj, At, Bt) do { __builtin_amdgcn_s_setprio(1); _Pragma("unroll") for (int m = 0; m < 4; ++m) _Pragma("unroll") for (int n = 0; n < 2; ++n) _Pragma("unroll") for (int k = 0; k < 2; ++k) \
;         acc[ai][bj][m][n] = __builtin_amdgcn_mfma_f32_16x16x32_bf16(Bt[n][k], At[m][k], acc[ai][bj][m][n], 0, 0, 0); __builtin_amdgcn_s_setprio(0); } while (0)
; #define PG8_WAIT_V(n) asm volatile("s_waitcnt vmcnt(" #n ")" ::: "memory")
; #define PG8_WAIT_L(n) asm volatile("s_waitcnt lgkmcnt(" #n ")" ::: "memory")
; #define PG8_BAR __builtin_amdgcn_s_barrier()
; #define PG8_SCHED __builtin_amdgcn_sched_barrier(0)
; template <class Epi, class Sched, bool ALIGN_EPI = false, bool SP2 = false>
; __device__ __forceinline__ void gemm_phase(PG8_LAS unsigned char* lds, const Gemm g, const Sched& S, const Epi& E, const int wave0) {
;     ...
;             PG8_LDB(B0, 1, 0); PG8_LDB(B1, 1, 1); PG8_SCHED; PG8_LDA(At, 1, 0); PG8_STAGE(PG8_SA(0, 1), a2 + hstep, voffA);
;             PG8_WAIT_V(8); PG8_WAIT_L(0); PG8_BAR; PG8_MMA(0, 0, At, B0); PG8_MMA(0, 1, At, B1); PG8_BAR; PG8_SCHED;
;             PG8_LDA(At, 1, 1); PG8_STAGE(PG8_SB(1, 0), b3, voffB); PG8_STAGE(PG8_SB(1, 1), b3 + hstep, voffB); PG8_STAGE(PG8_SA(1, 0), a3, voffA);
;             PG8_WAIT_V(8); PG8_WAIT_L(0); PG8_BAR; PG8_MMA(1, 0, At, B0); PG8_MMA(1, 1, At, B1); PG8_BAR; PG8_SCHED;
	s_add_i32 s18, s64, s95
	s_add_i32 m0, s18, 0xffffff80
	ds_read_b128 v[160:163], v245 offset:49152
	ds_read_b128 v[164:167], v245 offset:50176
	ds_read_b128 v[168:171], v245 offset:51200
	ds_read_b128 v[172:175], v245 offset:52224
	ds_read_b128 v[176:179], v245 offset:53248
	ds_read_b128 v[180:183], v245 offset:54272
	ds_read_b128 v[184:187], v245 offset:55296
	ds_read_b128 v[188:191], v245 offset:56320
	global_load_lds_dwordx4 v218, s[56:57] offset:128
	s_add_i32 m0, s18, 0x1f80
	s_add_u32 s18, s56, 0x40080
	s_addc_u32 s19, s57, 0
	global_load_lds_dwordx4 v222, s[56:57] offset:128
	s_add_i32 s56, s65, s95
	s_mov_b32 m0, s56
	s_nop 0
	global_load_lds_dwordx4 v218, s[18:19]
	s_add_i32 m0, s56, 0x2000
	s_nop 0
	global_load_lds_dwordx4 v222, s[18:19]
	s_add_i32 m0, s17, 0xffffff80
	s_nop 0
	global_load_lds_dwordx4 v216, s[58:59] offset:128
	s_add_i32 m0, s23, 0xffffff80
	s_nop 0
	global_load_lds_dwordx4 v220, s[58:59] offset:128
	s_waitcnt vmcnt(8)
	s_waitcnt lgkmcnt(0)
	s_barrier
	s_setprio 1
	v_mfma_f32_16x16x32_bf16 v[60:63], v[64:67], v[160:163], v[60:63]
	v_mfma_f32_16x16x32_bf16 v[52:55], v[136:139], v[160:163], v[52:55]
	v_mfma_f32_16x16x32_bf16 v[44:47], v[64:67], v[168:171], v[44:47]
	v_mfma_f32_16x16x32_bf16 v[36:39], v[136:139], v[168:171], v[36:39]
	v_mfma_f32_16x16x32_bf16 v[28:31], v[64:67], v[176:179], v[28:31]
	v_mfma_f32_16x16x32_bf16 v[20:23], v[136:139], v[176:179], v[20:23]
	v_mfma_f32_16x16x32_bf16 v[12:15], v[64:67], v[184:187], v[12:15]
	v_mfma_f32_16x16x32_bf16 v[4:7], v[136:139], v[184:187], v[4:7]
	v_mfma_f32_16x16x32_bf16 v[60:63], v[68:71], v[164:167], v[60:63]
	v_mfma_f32_16x16x32_bf16 v[52:55], v[140:143], v[164:167], v[52:55]
	v_mfma_f32_16x16x32_bf16 v[44:47], v[68:71], v[172:175], v[44:47]
	v_mfma_f32_16x16x32_bf16 v[36:39], v[140:143], v[172:175], v[36:39]
	v_mfma_f32_16x16x32_bf16 v[28:31], v[68:71], v[180:183], v[28:31]
	v_mfma_f32_16x16x32_bf16 v[20:23], v[140:143], v[180:183], v[20:23]
	v_mfma_f32_16x16x32_bf16 v[12:15], v[68:71], v[188:191], v[12:15]
	v_mfma_f32_16x16x32_bf16 v[4:7], v[140:143], v[188:191], v[4:7]
	v_mfma_f32_16x16x32_bf16 v[56:59], v[144:147], v[160:163], v[56:59]
	v_mfma_f32_16x16x32_bf16 v[48:51], v[152:155], v[160:163], v[48:51]
	v_mfma_f32_16x16x32_bf16 v[40:43], v[144:147], v[168:171], v[40:43]
	v_mfma_f32_16x16x32_bf16 v[32:35], v[152:155], v[168:171], v[32:35]
	v_mfma_f32_16x16x32_bf16 v[24:27], v[144:147], v[176:179], v[24:27]
	v_mfma_f32_16x16x32_bf16 v[16:19], v[152:155], v[176:179], v[16:19]
	v_mfma_f32_16x16x32_bf16 v[8:11], v[144:147], v[184:187], v[8:11]
	v_mfma_f32_16x16x32_bf16 v[0:3], v[152:155], v[184:187], v[0:3]
	v_mfma_f32_16x16x32_bf16 v[56:59], v[148:151], v[164:167], v[56:59]
	v_mfma_f32_16x16x32_bf16 v[48:51], v[156:159], v[164:167], v[48:51]
	v_mfma_f32_16x16x32_bf16 v[40:43], v[148:151], v[172:175], v[40:43]
	v_mfma_f32_16x16x32_bf16 v[32:35], v[156:159], v[172:175], v[32:35]
	v_mfma_f32_16x16x32_bf16 v[24:27], v[148:151], v[180:183], v[24:27]
	v_mfma_f32_16x16x32_bf16 v[16:19], v[156:159], v[180:183], v[16:19]
	v_mfma_f32_16x16x32_bf16 v[8:11], v[148:151], v[188:191], v[8:11]
	v_mfma_f32_16x16x32_bf16 v[0:3], v[156:159], v[188:191], v[0:3]
	s_setprio 0
	s_barrier
	s_add_i32 s63, s63, 2
	s_add_u32 s10, s10, 0x100
	s_addc_u32 s11, s11, 0
	s_add_u32 s61, s61, 0x100
	s_addc_u32 s62, s62, 0
	s_cmp_gt_u32 s63, 13

; __device__ __forceinline__ unsigned cvtpk(float lo, float hi) { f32x2 v = {lo, hi}; bf16x2_t b = __builtin_convertvector(v, bf16x2_t); return __builtin_bit_cast(unsigned, b); }
;     __device__ __forceinline__ void operator()(const pg8::f32x4 (&acc)[2][2][4][2], const pg8::Unit& u, int wr, int wc, int fr, int fq) const {
;         const int kind = p->kind, ldc = p->ldc, ncols = p->ncols, flags = p->flags; const float coef = p->coef;
;         const float* fin = (const float*)p->fin; float* fout = (float*)p->fout; bf16_t* o0 = (bf16_t*)p->o0; bf16_t* o1 = (bf16_t*)p->o1; const float* aux = (const float*)p->aux;
;         const int rowb = u.pm * 256 + wr * 64 + fr;
;         const int colb = u.pn * 256 + wc * 32 + (PERM ? 8 : 4) * fq;
;         constexpr int NS = PERM ? 4 : 16;
;         if (kind == EK_ACT) {
;     ...
;         } else if (kind == EK_BF16 && PERM) {
; #pragma unroll
;             for (int bj = 0; bj < 2; ++bj) {
;                 const int c = colb + 128 * bj;
;                 if (c < ncols) {
; #pragma unroll
;                     for (int ai = 0; ai < 2; ++ai)
; #pragma unroll
;                         for (int m = 0; m < 4; ++m) {
;                             pg8::f32x4 v0 = acc[ai][bj][m][0], v1 = acc[ai][bj][m][1];
;                             if (flags & 4) { const float rs = __builtin_amdgcn_rsqf(fin[rowb + 128 * ai + 16 * m] * (1.0f / DM) + EPS); v0 = v0 * rs; v1 = v1 * rs; }
;                             *(u32x4*)(o0 + (size_t)(rowb + 128 * ai + 16 * m) * ldc + c) = (u32x4){cvtpk(v0[0], v0[1]), cvtpk(v0[2], v0[3]), cvtpk(v1[0], v1[1]), cvtpk(v1[2], v1[3])};
;                         }
.LBB0_1143:
	v_mov_b32_e32 v64, v192
	v_mov_b32_e32 v65, v193
	v_mov_b32_e32 v66, v194
	v_mov_b32_e32 v67, v195
	v_mov_b32_e32 v68, v196
	v_mov_b32_e32 v69, v197
	v_mov_b32_e32 v70, v198
	v_mov_b32_e32 v71, v199
	v_mov_b32_e32 v136, v200
	v_mov_b32_e32 v137, v201
	v_mov_b32_e32 v138, v202
	v_mov_b32_e32 v139, v203
	v_lshl_add_u32 v228, s8, 8, v252
	s_mov_b64 s[8:9], -1
	v_readfirstlane_b32 s47, v192
	s_cmp_lt_i32 s47, 1
	s_cbranch_scc1 .LBB0_1235
	v_lshl_or_b32 v230, s54, 8, v248
	s_cmp_lt_i32 s47, 2
	s_cbranch_scc1 .LBB0_1184
	s_cmp_eq_u32 s47, 2
	s_cbranch_scc0 .LBB0_1183
	v_and_b32_e32 v64, 4, v67
	v_cmp_ne_u32_e64 s[8:9], 0, v64
	v_cmp_lt_i32_e32 vcc, v230, v66
	s_nop 0
	v_cndmask_b32_e64 v64, 0, 1, s[8:9]
	v_cmp_ne_u32_e64 s[8:9], 1, v64
	s_and_saveexec_b64 s[10:11], vcc
	s_cbranch_execz .LBB0_1164
	v_ashrrev_i32_e32 v229, 31, v228
	v_mov_b64_e32 v[142:143], v[134:135]
	v_mov_b64_e32 v[146:147], v[130:131]
	s_and_b64 vcc, exec, s[8:9]
	v_lshl_add_u64 v[150:151], v[228:229], 2, v[136:137]
	v_mov_b64_e32 v[140:141], v[132:133]
	v_mov_b64_e32 v[144:145], v[128:129]
	s_cbranch_vccnz .Lepi_pre_skip_1
	global_load_dword v152, v[150:151], off
	global_load_dword v153, v[150:151], off offset:64
	global_load_dword v154, v[150:151], off offset:128
	global_load_dword v155, v[150:151], off offset:192
	global_load_dword v156, v[150:151], off offset:512
	global_load_dword v157, v[150:151], off offset:576
	global_load_dword v158, v[150:151], off offset:640
	global_load_dword v159, v[150:151], off offset:704
	s_waitcnt vmcnt(0)
